# grid barrier: XCD leaders arrive with a no-return add on the cross-XCD counter and every workgroup polls that counter (no generation word, no returning add)
# baseline (speedup 1.0000x reference)
.LBB0_32:
	s_or_b64 exec, exec, s[22:23]
	v_cvt_f32_u32_e32 v5, v3
	s_waitcnt vmcnt(0)
	v_readfirstlane_b32 s2, v4
	v_sub_u32_e32 v4, 0, v3
	v_rcp_iflag_f32_e32 v5, v5
	v_add_u32_e32 v6, s2, v0
	v_mul_f32_e32 v5, 0x4f7ffffe, v5
	v_cvt_u32_f32_e32 v5, v5
	v_mul_lo_u32 v0, v4, v5
	v_mul_hi_u32 v0, v5, v0
	v_add_u32_e32 v0, v5, v0
	v_mul_hi_u32 v0, v6, v0
	v_mul_lo_u32 v4, v0, v3
	v_sub_u32_e32 v4, v6, v4
	v_add_u32_e32 v5, 1, v0
	v_cmp_ge_u32_e32 vcc, v4, v3
	s_nop 1
	v_cndmask_b32_e32 v0, v0, v5, vcc
	v_sub_u32_e32 v5, v4, v3
	v_cndmask_b32_e32 v4, v4, v5, vcc
	v_add_u32_e32 v5, 1, v0
	v_cmp_ge_u32_e32 vcc, v4, v3
	v_add_u32_e32 v4, 1, v6
	s_nop 0
	v_cndmask_b32_e32 v0, v0, v5, vcc
	v_mul_lo_u32 v5, v3, v0
	v_add_u32_e32 v3, v5, v3
	v_cmp_ne_u32_e32 vcc, v4, v3
	s_and_saveexec_b64 s[22:23], vcc
	s_xor_b64 s[22:23], exec, s[22:23]
	s_cbranch_execz .LBB0_46
	s_waitcnt lgkmcnt(0)
	v_mad_u32_u24 v6, v2, v0, v2
	v_readlane_b32 s24, v251, 11
	v_readlane_b32 s25, v251, 12
	s_mov_b32 s2, 0
	s_nop 4
.Lxb1_poll_n:
	global_load_dword v4, v1, s[24:25] sc1
	s_add_i32 s2, s2, 1
	s_waitcnt vmcnt(0)
	v_sub_u32_e32 v4, v4, v6
	v_cmp_gt_i32_e32 vcc, 0, v4
	s_cbranch_vccz .Lxb1_done_n
	s_cmp_lt_u32 s2, 0x200000
	s_cbranch_scc1 .Lxb1_poll_n
.Lxb1_done_n:
	buffer_inv sc1
	s_waitcnt vmcnt(0)
.LBB0_46:
	s_andn2_saveexec_b64 s[22:23], s[22:23]
	s_cbranch_execz .LBB0_66
	buffer_wbl2 sc1
	s_waitcnt lgkmcnt(0)
	v_mad_u32_u24 v6, v2, v0, v2
	v_readlane_b32 s24, v251, 11
	v_readlane_b32 s25, v251, 12
	v_mov_b32_e32 v5, 1
	s_mov_b32 s2, 0
	s_waitcnt vmcnt(0)
	s_nop 4
	global_atomic_add v1, v5, s[24:25]

.LBB0_771:
	s_or_b64 exec, exec, s[22:23]
	v_cvt_f32_u32_e32 v5, v3
	s_waitcnt vmcnt(0)
	v_readfirstlane_b32 s2, v4
	v_sub_u32_e32 v4, 0, v3
	v_rcp_iflag_f32_e32 v5, v5
	v_add_u32_e32 v6, s2, v0
	v_mul_f32_e32 v5, 0x4f7ffffe, v5
	v_cvt_u32_f32_e32 v5, v5
	v_mul_lo_u32 v0, v4, v5
	v_mul_hi_u32 v0, v5, v0
	v_add_u32_e32 v0, v5, v0
	v_mul_hi_u32 v0, v6, v0
	v_mul_lo_u32 v4, v0, v3
	v_sub_u32_e32 v4, v6, v4
	v_add_u32_e32 v5, 1, v0
	v_cmp_ge_u32_e32 vcc, v4, v3
	s_nop 1
	v_cndmask_b32_e32 v0, v0, v5, vcc
	v_sub_u32_e32 v5, v4, v3
	v_cndmask_b32_e32 v4, v4, v5, vcc
	v_add_u32_e32 v5, 1, v0
	v_cmp_ge_u32_e32 vcc, v4, v3
	v_add_u32_e32 v4, 1, v6
	s_nop 0
	v_cndmask_b32_e32 v0, v0, v5, vcc
	v_mul_lo_u32 v5, v3, v0
	v_add_u32_e32 v3, v5, v3
	v_cmp_ne_u32_e32 vcc, v4, v3
	s_and_saveexec_b64 s[16:17], vcc
	s_xor_b64 s[22:23], exec, s[16:17]
	s_cbranch_execz .LBB0_785
	s_waitcnt lgkmcnt(0)
	v_mad_u32_u24 v6, v2, v0, v2
	v_readlane_b32 s16, v251, 11
	v_readlane_b32 s17, v251, 12
	s_mov_b32 s2, 0
	s_nop 4
.Lxb2_poll_n:
	global_load_dword v4, v1, s[16:17] sc1
	s_add_i32 s2, s2, 1
	s_waitcnt vmcnt(0)
	v_sub_u32_e32 v4, v4, v6
	v_cmp_gt_i32_e32 vcc, 0, v4
	s_cbranch_vccz .Lxb2_done_n
	s_cmp_lt_u32 s2, 0x200000
	s_cbranch_scc1 .Lxb2_poll_n

.LBB0_785:
	s_andn2_saveexec_b64 s[16:17], s[22:23]
	s_cbranch_execz .LBB0_805
	buffer_wbl2 sc1
	s_waitcnt lgkmcnt(0)
	v_mad_u32_u24 v6, v2, v0, v2
	v_readlane_b32 s22, v251, 11
	v_readlane_b32 s23, v251, 12
	v_mov_b32_e32 v5, 1
	s_mov_b32 s2, 0
	s_waitcnt vmcnt(0)
	s_nop 4
	global_atomic_add v1, v5, s[22:23]
.Lxb2_poll_l:
	global_load_dword v4, v1, s[22:23] sc1
	s_add_i32 s2, s2, 1
	s_waitcnt vmcnt(0)
	v_sub_u32_e32 v4, v4, v6
	v_cmp_gt_i32_e32 vcc, 0, v4
	s_cbranch_vccz .Lxb2_done_l
	s_cmp_lt_u32 s2, 0x200000
	s_cbranch_scc1 .Lxb2_poll_l
